# context-attention tasks: Q fragment loads issued before the LDS staging so their latency hides behind it (confirmed with attention phases repeated 4x)
# baseline (speedup 1.0000x reference)
.LBB0_524:
	s_and_b32 s0, s2, 0xffffff00
	s_and_b32 s1, s11, 0xf0
	v_or_b32_e32 v0, s1, v118
	s_and_b32 s18, s4, 0x3c0
	s_ashr_i32 s1, s0, 31
	s_lshl_b32 s6, s18, 1
	s_lshl_b64 s[16:17], s[0:1], 12
	s_add_u32 s16, s44, s16
	v_or_b32_e32 v34, s0, v0
	s_addc_u32 s17, s45, s17
	v_ashrrev_i32_e32 v35, 31, v34
	s_add_u32 s16, s16, s6
	v_lshlrev_b64 v[0:1], 12, v[34:35]
	s_addc_u32 s17, s17, 0
	v_lshl_add_u64 v[0:1], s[44:45], 0, v[0:1]
	v_lshl_add_u64 v[40:41], s[16:17], 0, v[148:149]
	s_movk_i32 s16, 0x4000
	v_lshl_add_u64 v[0:1], v[0:1], 0, s[6:7]
	v_add_co_u32_e32 v12, vcc, s16, v40
	v_lshl_add_u64 v[4:5], v[36:37], 1, v[0:1]
	s_nop 0
	v_addc_co_u32_e32 v13, vcc, 0, v41, vcc
	global_load_dwordx4 v[0:3], v[4:5], off
	s_nop 0
	global_load_dwordx4 v[4:7], v[4:5], off offset:64
	s_barrier
	s_lshr_b32 s16, s2, 8
	s_lshl_b32 s0, s16, 9
	s_lshl_b32 s16, s16, 20
	s_bfe_u32 s17, s2, 0x40004
	s_lshl_b32 s1, s17, 7
	s_add_i32 s16, s16, s1
	s_addk_i32 s16, 0x800
	s_mul_i32 s17, s17, 0x480000
	s_add_i32 s0, s0, s17
	s_add_u32 s16, s44, s16
	s_addc_u32 s17, s45, 0
	s_add_u32 s0, s46, s0
	s_addc_u32 s1, s47, 0
	v_mov_b32_e32 v224, v248
	v_ashrrev_i32_e32 v224, 3, v224
	v_lshl_add_u32 v222, v224, 12, v252
	global_load_dwordx4 v[190:193], v222, s[16:17]
	v_mul_u32_u24_e32 v224, 0x90, v224
	v_add_u32_e32 v224, v224, v252
	v_add_u32_e32 v225, 0x200, v248
	v_ashrrev_i32_e32 v225, 3, v225
	v_lshl_add_u32 v222, v225, 12, v252
	global_load_dwordx4 v[194:197], v222, s[16:17]
	v_mul_u32_u24_e32 v225, 0x90, v225
	v_add_u32_e32 v225, v225, v252
	v_add_u32_e32 v226, 0x400, v248
	v_ashrrev_i32_e32 v226, 3, v226
	v_lshl_add_u32 v222, v226, 12, v252
	global_load_dwordx4 v[198:201], v222, s[16:17]
	v_mul_u32_u24_e32 v226, 0x90, v226
	v_add_u32_e32 v226, v226, v252
	v_add_u32_e32 v227, 0x600, v248
	v_ashrrev_i32_e32 v227, 3, v227
	v_lshl_add_u32 v222, v227, 12, v252
	global_load_dwordx4 v[202:205], v222, s[16:17]
	v_mul_u32_u24_e32 v227, 0x90, v227
	v_add_u32_e32 v227, v227, v252
	v_mov_b32_e32 v228, v248
	v_ashrrev_i32_e32 v228, 5, v228
	v_mul_u32_u24_e32 v222, 0x12000, v228
	v_add_u32_e32 v222, v222, v253
	global_load_dwordx4 v[206:209], v222, s[0:1]
	v_mul_u32_u24_e32 v228, 0x210, v228
	v_add_u32_e32 v228, v228, v253
	v_add_u32_e32 v229, 0x200, v248
	v_ashrrev_i32_e32 v229, 5, v229
	v_mul_u32_u24_e32 v222, 0x12000, v229
	v_add_u32_e32 v222, v222, v253
	global_load_dwordx4 v[210:213], v222, s[0:1]
	v_mul_u32_u24_e32 v229, 0x210, v229
	v_add_u32_e32 v229, v229, v253
	v_add_u32_e32 v230, 0x400, v248
	v_ashrrev_i32_e32 v230, 5, v230
	v_mul_u32_u24_e32 v222, 0x12000, v230
	v_add_u32_e32 v222, v222, v253
	global_load_dwordx4 v[214:217], v222, s[0:1]
	v_mul_u32_u24_e32 v230, 0x210, v230
	v_add_u32_e32 v230, v230, v253
	v_add_u32_e32 v231, 0x600, v248
	v_ashrrev_i32_e32 v231, 5, v231
	v_mul_u32_u24_e32 v222, 0x12000, v231
	v_add_u32_e32 v222, v222, v253
	global_load_dwordx4 v[218:221], v222, s[0:1]
	v_mul_u32_u24_e32 v231, 0x210, v231
	v_add_u32_e32 v231, v231, v253
	s_waitcnt vmcnt(7)
	ds_write_b128 v224, v[190:193]
	s_waitcnt vmcnt(6)
	ds_write_b128 v225, v[194:197]
	s_waitcnt vmcnt(5)
	ds_write_b128 v226, v[198:201]
	s_waitcnt vmcnt(4)
	ds_write_b128 v227, v[202:205]
	s_waitcnt vmcnt(3)
	ds_write_b128 v228, v[206:209] offset:36864
	s_waitcnt vmcnt(2)
	ds_write_b128 v229, v[210:213] offset:36864
	s_waitcnt vmcnt(1)
	ds_write_b128 v230, v[214:217] offset:36864
	s_waitcnt vmcnt(0)
	ds_write_b128 v231, v[218:221] offset:36864
	s_waitcnt lgkmcnt(0)
	s_barrier
	ds_read_b128 v[190:193], v246
	ds_read_b128 v[194:197], v246 offset:64
	ds_read_b128 v[198:201], v246 offset:576
	ds_read_b128 v[202:205], v246 offset:640
	ds_read_b128 v[206:209], v246 offset:4608
	ds_read_b128 v[210:213], v246 offset:4672
	ds_read_b128 v[214:217], v246 offset:5184
	ds_read_b128 v[218:221], v246 offset:5248
	ds_read_b128 v[222:225], v246 offset:9216
	ds_read_b128 v[226:229], v246 offset:9280
	ds_read_b128 v[230:233], v246 offset:9792
	ds_read_b128 v[234:237], v246 offset:9856
	ds_read_b128 v[238:241], v246 offset:13824
	ds_read_b128 v[242:245], v246 offset:13888
	s_nop 0
	s_nop 0
	s_nop 0
	s_mul_i32 s18, s18, 0x12000
	s_add_u32 s16, s46, s18
	s_addc_u32 s17, s47, 0
	s_waitcnt vmcnt(0)
	s_waitcnt lgkmcnt(13)
	v_mfma_f32_16x16x32_bf16 v[20:23], v[190:193], v[0:3], 0
	s_waitcnt lgkmcnt(12)
	v_mfma_f32_16x16x32_bf16 v[16:19], v[194:197], v[4:7], v[20:23]
	ds_read_b128 v[190:193], v246 offset:14400
	ds_read_b128 v[194:197], v246 offset:14464
	s_nop 7
	v_pk_mul_f32 v[74:75], v[18:19], s[12:13] op_sel_hi:[1,0]
	v_pk_mul_f32 v[76:77], v[16:17], s[12:13] op_sel_hi:[1,0]
	v_max_f32_e32 v16, v74, v75
	v_max3_f32 v24, v76, v77, v16
	s_nop 1
	s_nop 0
	s_waitcnt lgkmcnt(13)
	v_mfma_f32_16x16x32_bf16 v[8:11], v[198:201], v[0:3], 0
	s_waitcnt lgkmcnt(12)
	v_mfma_f32_16x16x32_bf16 v[8:11], v[202:205], v[4:7], v[8:11]
	ds_read_b128 v[198:201], v246 offset:18432
	ds_read_b128 v[202:205], v246 offset:18496
	s_nop 7
	v_pk_mul_f32 v[70:71], v[10:11], s[12:13] op_sel_hi:[1,0]
	v_pk_mul_f32 v[72:73], v[8:9], s[12:13] op_sel_hi:[1,0]
	v_max_f32_e32 v8, v70, v71
	v_max3_f32 v8, v72, v73, v8
	v_max3_f32 v24, v24, s69, v8
	s_nop 1
	s_nop 0
	s_waitcnt lgkmcnt(13)
	v_mfma_f32_16x16x32_bf16 v[16:19], v[206:209], v[0:3], 0
	s_waitcnt lgkmcnt(12)
	v_mfma_f32_16x16x32_bf16 v[16:19], v[210:213], v[4:7], v[16:19]
	ds_read_b128 v[206:209], v246 offset:19008
	ds_read_b128 v[210:213], v246 offset:19072
	s_nop 7
	v_pk_mul_f32 v[66:67], v[18:19], s[12:13] op_sel_hi:[1,0]
	v_pk_mul_f32 v[68:69], v[16:17], s[12:13] op_sel_hi:[1,0]
	v_max_f32_e32 v16, v66, v67
	v_max3_f32 v25, v68, v69, v16
	s_nop 1
	s_nop 0
	s_waitcnt lgkmcnt(13)
	v_mfma_f32_16x16x32_bf16 v[8:11], v[214:217], v[0:3], 0
	s_waitcnt lgkmcnt(12)
	v_mfma_f32_16x16x32_bf16 v[8:11], v[218:221], v[4:7], v[8:11]
	ds_read_b128 v[214:217], v246 offset:23040
	ds_read_b128 v[218:221], v246 offset:23104
	s_nop 7
	v_pk_mul_f32 v[62:63], v[10:11], s[12:13] op_sel_hi:[1,0]
	v_pk_mul_f32 v[64:65], v[8:9], s[12:13] op_sel_hi:[1,0]
	v_max_f32_e32 v8, v62, v63
	v_max3_f32 v8, v64, v65, v8
	v_max3_f32 v24, v24, v25, v8
	s_nop 1
	s_nop 0
	s_waitcnt lgkmcnt(13)
	v_mfma_f32_16x16x32_bf16 v[16:19], v[222:225], v[0:3], 0
	s_waitcnt lgkmcnt(12)
	v_mfma_f32_16x16x32_bf16 v[16:19], v[226:229], v[4:7], v[16:19]
	ds_read_b128 v[222:225], v246 offset:23616
	ds_read_b128 v[226:229], v246 offset:23680
	s_nop 7
	v_pk_mul_f32 v[58:59], v[18:19], s[12:13] op_sel_hi:[1,0]
	v_pk_mul_f32 v[60:61], v[16:17], s[12:13] op_sel_hi:[1,0]
	v_max_f32_e32 v16, v58, v59
	v_max3_f32 v25, v60, v61, v16
	s_nop 1
	s_nop 0
	s_waitcnt lgkmcnt(13)
	v_mfma_f32_16x16x32_bf16 v[8:11], v[230:233], v[0:3], 0
	s_waitcnt lgkmcnt(12)
	v_mfma_f32_16x16x32_bf16 v[8:11], v[234:237], v[4:7], v[8:11]
	ds_read_b128 v[230:233], v246 offset:27648
	ds_read_b128 v[234:237], v246 offset:27712
	s_nop 7
	v_pk_mul_f32 v[54:55], v[10:11], s[12:13] op_sel_hi:[1,0]
	v_pk_mul_f32 v[56:57], v[8:9], s[12:13] op_sel_hi:[1,0]
	v_max_f32_e32 v8, v54, v55
	v_max3_f32 v8, v56, v57, v8
	v_max3_f32 v24, v24, v25, v8
	s_nop 1
	s_nop 0
	s_waitcnt lgkmcnt(13)
	v_mfma_f32_16x16x32_bf16 v[16:19], v[238:241], v[0:3], 0
	s_waitcnt lgkmcnt(12)
	v_mfma_f32_16x16x32_bf16 v[16:19], v[242:245], v[4:7], v[16:19]
	ds_read_b128 v[238:241], v246 offset:28224
	ds_read_b128 v[242:245], v246 offset:28288
	s_nop 7
	v_pk_mul_f32 v[50:51], v[18:19], s[12:13] op_sel_hi:[1,0]
	v_pk_mul_f32 v[52:53], v[16:17], s[12:13] op_sel_hi:[1,0]
	v_max_f32_e32 v16, v50, v51
	v_max3_f32 v25, v52, v53, v16
	s_nop 1
	s_nop 0
	s_waitcnt lgkmcnt(13)
	v_mfma_f32_16x16x32_bf16 v[8:11], v[190:193], v[0:3], 0
	s_waitcnt lgkmcnt(12)
	v_mfma_f32_16x16x32_bf16 v[8:11], v[194:197], v[4:7], v[8:11]
	ds_read_b128 v[190:193], v246 offset:32256
	ds_read_b128 v[194:197], v246 offset:32320
	s_nop 7
	v_pk_mul_f32 v[46:47], v[10:11], s[12:13] op_sel_hi:[1,0]
	v_pk_mul_f32 v[48:49], v[8:9], s[12:13] op_sel_hi:[1,0]
	v_max_f32_e32 v8, v46, v47
	v_max3_f32 v8, v48, v49, v8
	v_max3_f32 v24, v24, v25, v8
	s_nop 1
	s_nop 0
	s_waitcnt lgkmcnt(13)
	v_mfma_f32_16x16x32_bf16 v[16:19], v[198:201], v[0:3], 0
	s_waitcnt lgkmcnt(12)
	v_mfma_f32_16x16x32_bf16 v[16:19], v[202:205], v[4:7], v[16:19]
	ds_read_b128 v[198:201], v246 offset:32832
	ds_read_b128 v[202:205], v246 offset:32896
	s_nop 7
	v_pk_mul_f32 v[42:43], v[18:19], s[12:13] op_sel_hi:[1,0]
	v_pk_mul_f32 v[44:45], v[16:17], s[12:13] op_sel_hi:[1,0]
	v_max_f32_e32 v16, v42, v43
	v_max3_f32 v25, v44, v45, v16
	s_nop 1
	s_nop 0
	s_waitcnt lgkmcnt(13)
	v_mfma_f32_16x16x32_bf16 v[8:11], v[206:209], v[0:3], 0
	s_waitcnt lgkmcnt(12)
	v_mfma_f32_16x16x32_bf16 v[8:11], v[210:213], v[4:7], v[8:11]
	s_nop 7
	v_pk_mul_f32 v[28:29], v[10:11], s[12:13] op_sel_hi:[1,0]
	v_pk_mul_f32 v[30:31], v[8:9], s[12:13] op_sel_hi:[1,0]
	v_max_f32_e32 v8, v28, v29
	v_max3_f32 v8, v30, v31, v8
	v_max3_f32 v84, v24, v25, v8
	s_nop 1
	s_nop 0
	s_waitcnt lgkmcnt(11)
	v_mfma_f32_16x16x32_bf16 v[16:19], v[214:217], v[0:3], 0
	s_waitcnt lgkmcnt(10)
	v_mfma_f32_16x16x32_bf16 v[16:19], v[218:221], v[4:7], v[16:19]
	s_nop 7
	v_pk_mul_f32 v[24:25], v[18:19], s[12:13] op_sel_hi:[1,0]
	v_pk_mul_f32 v[26:27], v[16:17], s[12:13] op_sel_hi:[1,0]
	v_max_f32_e32 v16, v24, v25
	v_max3_f32 v85, v26, v27, v16
	s_nop 1
	s_waitcnt lgkmcnt(9)
	v_mfma_f32_16x16x32_bf16 v[8:11], v[222:225], v[0:3], 0
	s_waitcnt lgkmcnt(8)
	v_mfma_f32_16x16x32_bf16 v[10:13], v[226:229], v[4:7], v[8:11]
	s_nop 7
	v_pk_mul_f32 v[8:9], v[12:13], s[12:13] op_sel_hi:[1,0]
	v_pk_mul_f32 v[22:23], v[10:11], s[12:13] op_sel_hi:[1,0]
	v_max_f32_e32 v10, v8, v9
	v_max3_f32 v10, v22, v23, v10
	v_max3_f32 v92, v84, v85, v10
	s_nop 1
	s_waitcnt lgkmcnt(7)
	v_mfma_f32_16x16x32_bf16 v[16:19], v[230:233], v[0:3], 0
	s_waitcnt lgkmcnt(6)
	v_mfma_f32_16x16x32_bf16 v[16:19], v[234:237], v[4:7], v[16:19]
	s_nop 7
	v_pk_mul_f32 v[10:11], v[18:19], s[12:13] op_sel_hi:[1,0]
	v_pk_mul_f32 v[16:17], v[16:17], s[12:13] op_sel_hi:[1,0]
	v_max_f32_e32 v18, v10, v11
	v_max3_f32 v93, v16, v17, v18
	s_nop 1
	s_waitcnt lgkmcnt(5)
	v_mfma_f32_16x16x32_bf16 v[12:15], v[238:241], v[0:3], 0
	s_waitcnt lgkmcnt(4)
	v_mfma_f32_16x16x32_bf16 v[18:21], v[242:245], v[4:7], v[12:15]
	s_nop 7
	v_pk_mul_f32 v[12:13], v[20:21], s[12:13] op_sel_hi:[1,0]
	v_pk_mul_f32 v[18:19], v[18:19], s[12:13] op_sel_hi:[1,0]
	v_max_f32_e32 v14, v12, v13
	v_max3_f32 v14, v18, v19, v14
	v_max3_f32 v96, v92, v93, v14
	s_nop 1
	s_waitcnt lgkmcnt(3)
	v_mfma_f32_16x16x32_bf16 v[80:83], v[190:193], v[0:3], 0
	s_waitcnt lgkmcnt(2)
	v_mfma_f32_16x16x32_bf16 v[80:83], v[194:197], v[4:7], v[80:83]
	s_nop 7
	v_pk_mul_f32 v[14:15], v[82:83], s[12:13] op_sel_hi:[1,0]
	v_pk_mul_f32 v[20:21], v[80:81], s[12:13] op_sel_hi:[1,0]
	v_max_f32_e32 v40, v14, v15
	v_max3_f32 v40, v20, v21, v40
	s_waitcnt lgkmcnt(1)
	v_mfma_f32_16x16x32_bf16 v[0:3], v[198:201], v[0:3], 0
	s_waitcnt lgkmcnt(0)
	v_mfma_f32_16x16x32_bf16 v[2:5], v[202:205], v[4:7], v[0:3]
	s_nop 7
	v_pk_mul_f32 v[0:1], v[4:5], s[12:13] op_sel_hi:[1,0]
	v_pk_mul_f32 v[2:3], v[2:3], s[12:13] op_sel_hi:[1,0]
	v_max_f32_e32 v4, v0, v1
	v_max3_f32 v4, v2, v3, v4
	v_max3_f32 v4, v96, v40, v4
	ds_bpermute_b32 v5, v78, v4
	s_lshl_b64 s[0:1], s[0:1], 1
	s_add_u32 s0, s16, s0
	s_addc_u32 s1, s17, s1
	v_lshl_add_u64 v[40:41], s[0:1], 0, v[32:33]
	ds_read_b128 v[190:193], v247 offset:36864
	ds_read_b128 v[194:197], v247 offset:45312
	ds_read_b128 v[198:201], v247 offset:53760
	ds_read_b128 v[202:205], v247 offset:62208
	ds_read_b128 v[206:209], v247 offset:36928
	ds_read_b128 v[210:213], v247 offset:45376
	ds_read_b128 v[214:217], v247 offset:53824
	ds_read_b128 v[218:221], v247 offset:62272
	ds_read_b128 v[222:225], v247 offset:36992
	ds_read_b128 v[226:229], v247 offset:45440
	ds_read_b128 v[230:233], v247 offset:53888
	ds_read_b128 v[234:237], v247 offset:62336
	s_waitcnt lgkmcnt(0)
	v_max_f32_e32 v5, v5, v5
	v_max_f32_e32 v4, v4, v5
	ds_bpermute_b32 v5, v79, v4
	s_mov_b32 s0, 0x240000
	s_waitcnt lgkmcnt(0)
	v_max_f32_e32 v5, v5, v5
	v_max_f32_e32 v4, v4, v5
	v_sub_f32_e32 v6, v77, v4
	v_mul_f32_e32 v6, 0x3fb8aa3b, v6
	v_exp_f32_e32 v77, v6
	v_sub_f32_e32 v6, v74, v4
	v_mul_f32_e32 v6, 0x3fb8aa3b, v6
	v_exp_f32_e32 v74, v6
	v_sub_f32_e32 v6, v75, v4
	v_mul_f32_e32 v6, 0x3fb8aa3b, v6
	v_exp_f32_e32 v75, v6
	v_sub_f32_e32 v6, v72, v4
	v_mul_f32_e32 v6, 0x3fb8aa3b, v6
	v_exp_f32_e32 v72, v6
	v_sub_f32_e32 v6, v73, v4
	v_mul_f32_e32 v6, 0x3fb8aa3b, v6
	v_exp_f32_e32 v73, v6
	v_sub_f32_e32 v6, v70, v4
	v_mul_f32_e32 v6, 0x3fb8aa3b, v6
	v_exp_f32_e32 v70, v6
	v_sub_f32_e32 v6, v71, v4
	v_mul_f32_e32 v6, 0x3fb8aa3b, v6
	v_exp_f32_e32 v71, v6
	v_sub_f32_e32 v6, v68, v4
	v_mul_f32_e32 v6, 0x3fb8aa3b, v6
	v_exp_f32_e32 v68, v6
	v_sub_f32_e32 v6, v69, v4
	v_mul_f32_e32 v6, 0x3fb8aa3b, v6
	v_exp_f32_e32 v69, v6
	v_sub_f32_e32 v6, v66, v4
	v_mul_f32_e32 v6, 0x3fb8aa3b, v6
	v_exp_f32_e32 v66, v6
	v_sub_f32_e32 v6, v67, v4
	v_mul_f32_e32 v6, 0x3fb8aa3b, v6
	v_exp_f32_e32 v67, v6
	v_sub_f32_e32 v6, v64, v4
	v_mul_f32_e32 v6, 0x3fb8aa3b, v6
	v_exp_f32_e32 v64, v6
	v_sub_f32_e32 v6, v65, v4
	v_mul_f32_e32 v6, 0x3fb8aa3b, v6
	v_exp_f32_e32 v65, v6
	v_sub_f32_e32 v6, v62, v4
	v_mul_f32_e32 v6, 0x3fb8aa3b, v6
	v_exp_f32_e32 v62, v6
	v_sub_f32_e32 v6, v63, v4
	v_mul_f32_e32 v6, 0x3fb8aa3b, v6
	v_exp_f32_e32 v63, v6
	v_sub_f32_e32 v6, v60, v4
	v_mul_f32_e32 v6, 0x3fb8aa3b, v6
	v_exp_f32_e32 v60, v6
	v_sub_f32_e32 v6, v61, v4
	v_mul_f32_e32 v6, 0x3fb8aa3b, v6
	v_exp_f32_e32 v61, v6
	v_sub_f32_e32 v6, v58, v4
	v_mul_f32_e32 v6, 0x3fb8aa3b, v6
	v_exp_f32_e32 v58, v6
	v_sub_f32_e32 v6, v59, v4
	v_mul_f32_e32 v6, 0x3fb8aa3b, v6
	v_exp_f32_e32 v59, v6
	v_sub_f32_e32 v6, v56, v4
	v_mul_f32_e32 v6, 0x3fb8aa3b, v6
	v_exp_f32_e32 v56, v6
	v_sub_f32_e32 v6, v57, v4
	v_mul_f32_e32 v6, 0x3fb8aa3b, v6
	v_exp_f32_e32 v57, v6
	v_sub_f32_e32 v6, v54, v4
	v_mul_f32_e32 v6, 0x3fb8aa3b, v6
	v_exp_f32_e32 v54, v6
	v_sub_f32_e32 v6, v55, v4
	v_mul_f32_e32 v6, 0x3fb8aa3b, v6
	v_exp_f32_e32 v55, v6
	v_sub_f32_e32 v6, v52, v4
	v_mul_f32_e32 v6, 0x3fb8aa3b, v6
	v_exp_f32_e32 v52, v6
	v_sub_f32_e32 v6, v53, v4
	v_mul_f32_e32 v6, 0x3fb8aa3b, v6
	v_exp_f32_e32 v53, v6
	v_sub_f32_e32 v6, v50, v4
	v_mul_f32_e32 v6, 0x3fb8aa3b, v6
	v_exp_f32_e32 v50, v6
	v_sub_f32_e32 v6, v51, v4
	v_mul_f32_e32 v6, 0x3fb8aa3b, v6
	v_exp_f32_e32 v51, v6
	v_sub_f32_e32 v6, v48, v4
	v_mul_f32_e32 v6, 0x3fb8aa3b, v6
	v_exp_f32_e32 v48, v6
	v_sub_f32_e32 v6, v49, v4
	v_sub_f32_e32 v5, v76, v4
	v_mul_f32_e32 v6, 0x3fb8aa3b, v6
	v_mul_f32_e32 v5, 0x3fb8aa3b, v5
	v_exp_f32_e32 v49, v6
	v_sub_f32_e32 v6, v46, v4
	v_exp_f32_e32 v76, v5
	v_mul_f32_e32 v6, 0x3fb8aa3b, v6
	v_exp_f32_e32 v80, v6
	v_sub_f32_e32 v6, v47, v4
	v_mul_f32_e32 v6, 0x3fb8aa3b, v6
	v_exp_f32_e32 v81, v6
	v_sub_f32_e32 v6, v44, v4
	v_add_f32_e32 v5, 0, v76
	v_mul_f32_e32 v6, 0x3fb8aa3b, v6
	v_add_f32_e32 v5, v77, v5
	v_exp_f32_e32 v82, v6
	v_sub_f32_e32 v6, v45, v4
	v_add_f32_e32 v5, v74, v5
	v_mul_f32_e32 v6, 0x3fb8aa3b, v6
	v_add_f32_e32 v5, v75, v5
	v_exp_f32_e32 v83, v6
	v_sub_f32_e32 v6, v42, v4
	v_add_f32_e32 v5, v72, v5
	v_mul_f32_e32 v6, 0x3fb8aa3b, v6
	v_add_f32_e32 v5, v73, v5
	v_exp_f32_e32 v84, v6
	v_sub_f32_e32 v6, v43, v4
	v_add_f32_e32 v5, v70, v5
	v_mul_f32_e32 v6, 0x3fb8aa3b, v6
	v_add_f32_e32 v5, v71, v5
	v_exp_f32_e32 v85, v6
	v_sub_f32_e32 v6, v30, v4
	v_add_f32_e32 v5, v68, v5
	v_mul_f32_e32 v6, 0x3fb8aa3b, v6
	v_add_f32_e32 v5, v69, v5
	v_exp_f32_e32 v86, v6
	v_sub_f32_e32 v6, v31, v4
	v_add_f32_e32 v5, v66, v5
	v_mul_f32_e32 v6, 0x3fb8aa3b, v6
	v_add_f32_e32 v5, v67, v5
	v_exp_f32_e32 v87, v6
	v_sub_f32_e32 v6, v28, v4
	v_add_f32_e32 v5, v64, v5
	v_mul_f32_e32 v6, 0x3fb8aa3b, v6
	v_add_f32_e32 v5, v65, v5
	v_exp_f32_e32 v88, v6
	v_sub_f32_e32 v6, v29, v4
	v_add_f32_e32 v5, v62, v5
	v_mul_f32_e32 v6, 0x3fb8aa3b, v6
	v_add_f32_e32 v5, v63, v5
	v_exp_f32_e32 v89, v6
	v_sub_f32_e32 v6, v26, v4
	v_add_f32_e32 v5, v60, v5
	v_mul_f32_e32 v6, 0x3fb8aa3b, v6
	v_add_f32_e32 v5, v61, v5
	v_exp_f32_e32 v90, v6
	v_sub_f32_e32 v6, v27, v4
	v_add_f32_e32 v5, v58, v5
	v_mul_f32_e32 v6, 0x3fb8aa3b, v6
	v_add_f32_e32 v5, v59, v5
	v_exp_f32_e32 v91, v6
	v_sub_f32_e32 v6, v24, v4
	v_add_f32_e32 v5, v56, v5
	v_mul_f32_e32 v6, 0x3fb8aa3b, v6
	v_add_f32_e32 v5, v57, v5
	v_exp_f32_e32 v92, v6
	v_sub_f32_e32 v6, v25, v4
	v_add_f32_e32 v5, v54, v5
	v_mul_f32_e32 v6, 0x3fb8aa3b, v6
	v_add_f32_e32 v5, v55, v5
	v_exp_f32_e32 v93, v6
	v_sub_f32_e32 v6, v22, v4
	v_add_f32_e32 v5, v52, v5
	v_mul_f32_e32 v6, 0x3fb8aa3b, v6
	v_add_f32_e32 v5, v53, v5
	v_exp_f32_e32 v94, v6
	v_sub_f32_e32 v6, v23, v4
	v_add_f32_e32 v5, v50, v5
	v_mul_f32_e32 v6, 0x3fb8aa3b, v6
	v_add_f32_e32 v5, v51, v5
	v_exp_f32_e32 v95, v6
	v_sub_f32_e32 v6, v8, v4
	v_add_f32_e32 v5, v48, v5
	v_mul_f32_e32 v6, 0x3fb8aa3b, v6
	v_add_f32_e32 v5, v49, v5
	v_exp_f32_e32 v97, v6
	v_sub_f32_e32 v6, v9, v4
	v_add_f32_e32 v5, v80, v5
	v_mul_f32_e32 v6, 0x3fb8aa3b, v6
	v_add_f32_e32 v5, v81, v5
	v_exp_f32_e32 v100, v6
	v_sub_f32_e32 v6, v16, v4
	v_add_f32_e32 v5, v82, v5
	v_mul_f32_e32 v6, 0x3fb8aa3b, v6
	v_add_f32_e32 v5, v83, v5
	v_exp_f32_e32 v96, v6
	v_sub_f32_e32 v6, v17, v4
	v_add_f32_e32 v5, v84, v5
	v_mul_f32_e32 v6, 0x3fb8aa3b, v6
	v_add_f32_e32 v5, v85, v5
	v_exp_f32_e32 v98, v6
	v_sub_f32_e32 v6, v10, v4
	v_add_f32_e32 v5, v86, v5
	v_mul_f32_e32 v6, 0x3fb8aa3b, v6
	v_add_f32_e32 v5, v87, v5
	v_exp_f32_e32 v99, v6
	v_sub_f32_e32 v6, v11, v4
	v_add_f32_e32 v5, v88, v5
	v_mul_f32_e32 v6, 0x3fb8aa3b, v6
	v_add_f32_e32 v5, v89, v5
	v_exp_f32_e32 v101, v6
	v_sub_f32_e32 v6, v18, v4
	v_add_f32_e32 v5, v90, v5
	v_mul_f32_e32 v6, 0x3fb8aa3b, v6
	v_add_f32_e32 v5, v91, v5
	v_exp_f32_e32 v102, v6
	v_sub_f32_e32 v6, v19, v4
	v_add_f32_e32 v5, v92, v5
	v_mul_f32_e32 v6, 0x3fb8aa3b, v6
	v_add_f32_e32 v5, v93, v5
	v_exp_f32_e32 v104, v6
	v_sub_f32_e32 v6, v12, v4
	v_add_f32_e32 v5, v94, v5
	v_mul_f32_e32 v6, 0x3fb8aa3b, v6
	v_add_f32_e32 v5, v95, v5
	v_exp_f32_e32 v105, v6
	v_sub_f32_e32 v6, v13, v4
	v_add_f32_e32 v5, v97, v5
	v_mul_f32_e32 v6, 0x3fb8aa3b, v6
	v_add_f32_e32 v5, v100, v5
	v_exp_f32_e32 v108, v6
	v_sub_f32_e32 v6, v20, v4
	v_add_f32_e32 v5, v96, v5
	v_mul_f32_e32 v6, 0x3fb8aa3b, v6
	v_add_f32_e32 v5, v98, v5
	v_exp_f32_e32 v103, v6
	v_sub_f32_e32 v6, v21, v4
	v_add_f32_e32 v5, v99, v5
	v_mul_f32_e32 v6, 0x3fb8aa3b, v6
	v_add_f32_e32 v5, v101, v5
	v_exp_f32_e32 v106, v6
	v_sub_f32_e32 v6, v14, v4
	v_add_f32_e32 v5, v102, v5
	v_mul_f32_e32 v6, 0x3fb8aa3b, v6
	v_add_f32_e32 v5, v104, v5
	v_exp_f32_e32 v107, v6
	v_sub_f32_e32 v6, v15, v4
	v_add_f32_e32 v5, v105, v5
	v_mul_f32_e32 v6, 0x3fb8aa3b, v6
	v_sub_f32_e32 v2, v2, v4
	v_add_f32_e32 v5, v108, v5
	v_exp_f32_e32 v109, v6
	v_mul_f32_e32 v2, 0x3fb8aa3b, v2
	v_sub_f32_e32 v3, v3, v4
	v_add_f32_e32 v5, v103, v5
	v_exp_f32_e32 v110, v2
	v_mul_f32_e32 v3, 0x3fb8aa3b, v3
	v_sub_f32_e32 v0, v0, v4
	v_add_f32_e32 v5, v106, v5
	v_exp_f32_e32 v111, v3
	v_mul_f32_e32 v0, 0x3fb8aa3b, v0
	v_sub_f32_e32 v1, v1, v4
	v_add_f32_e32 v5, v107, v5
	v_exp_f32_e32 v112, v0
	v_mul_f32_e32 v1, 0x3fb8aa3b, v1
	v_add_f32_e32 v5, v109, v5
	v_exp_f32_e32 v113, v1
	v_add_f32_e32 v2, v110, v5
	v_add_f32_e32 v2, v111, v2
	v_add_f32_e32 v0, v112, v2
	v_add_f32_e32 v0, v113, v0
	ds_bpermute_b32 v1, v78, v0
	s_nop 0
	s_mov_b32 s0, 0x360000
	s_nop 0
	s_waitcnt lgkmcnt(0)
	v_add_f32_e32 v114, v0, v1
	ds_bpermute_b32 v115, v79, v114
	v_cvt_pk_bf16_f32 v120, v76, v77
	v_cvt_pk_bf16_f32 v121, v74, v75
	v_cvt_pk_bf16_f32 v122, v72, v73
	v_cvt_pk_bf16_f32 v123, v70, v71
	s_waitcnt lgkmcnt(11)
	v_mfma_f32_16x16x32_bf16 v[0:3], v[190:193], v[120:123], 0
	s_waitcnt lgkmcnt(10)
	v_mfma_f32_16x16x32_bf16 v[4:7], v[194:197], v[120:123], 0
	s_waitcnt lgkmcnt(9)
	v_mfma_f32_16x16x32_bf16 v[8:11], v[198:201], v[120:123], 0
	s_waitcnt lgkmcnt(8)
	v_mfma_f32_16x16x32_bf16 v[20:23], v[202:205], v[120:123], 0
	ds_read_b128 v[190:193], v247 offset:37056
	ds_read_b128 v[194:197], v247 offset:45504
	ds_read_b128 v[198:201], v247 offset:53952
	ds_read_b128 v[202:205], v247 offset:62400
	v_cvt_pk_bf16_f32 v128, v68, v69
	v_cvt_pk_bf16_f32 v129, v66, v67
	v_cvt_pk_bf16_f32 v130, v64, v65
	v_cvt_pk_bf16_f32 v131, v62, v63
	s_waitcnt lgkmcnt(11)
	v_mfma_f32_16x16x32_bf16 v[0:3], v[206:209], v[128:131], v[0:3]
	s_waitcnt lgkmcnt(10)
	v_mfma_f32_16x16x32_bf16 v[4:7], v[210:213], v[128:131], v[4:7]
	s_waitcnt lgkmcnt(9)
	v_mfma_f32_16x16x32_bf16 v[8:11], v[214:217], v[128:131], v[8:11]
	s_waitcnt lgkmcnt(8)
	v_mfma_f32_16x16x32_bf16 v[12:15], v[218:221], v[128:131], v[20:23]
	ds_read_b128 v[206:209], v247 offset:37120
	ds_read_b128 v[210:213], v247 offset:45568
	ds_read_b128 v[214:217], v247 offset:54016
	ds_read_b128 v[218:221], v247 offset:62464
	s_nop 1
	v_cvt_pk_bf16_f32 v60, v60, v61
	v_cvt_pk_bf16_f32 v61, v58, v59
	v_cvt_pk_bf16_f32 v62, v56, v57
	v_cvt_pk_bf16_f32 v63, v54, v55
	s_waitcnt lgkmcnt(11)
	v_mfma_f32_16x16x32_bf16 v[0:3], v[222:225], v[60:63], v[0:3]
	s_waitcnt lgkmcnt(10)
	v_mfma_f32_16x16x32_bf16 v[4:7], v[226:229], v[60:63], v[4:7]
	s_waitcnt lgkmcnt(9)
	v_mfma_f32_16x16x32_bf16 v[8:11], v[230:233], v[60:63], v[8:11]
	s_waitcnt lgkmcnt(8)
	v_mfma_f32_16x16x32_bf16 v[12:15], v[234:237], v[60:63], v[12:15]
	ds_read_b128 v[222:225], v247 offset:37184
	ds_read_b128 v[226:229], v247 offset:45632
	ds_read_b128 v[230:233], v247 offset:54080
	ds_read_b128 v[234:237], v247 offset:62528
	v_cvt_pk_bf16_f32 v70, v52, v53
	v_cvt_pk_bf16_f32 v71, v50, v51
	v_cvt_pk_bf16_f32 v72, v48, v49
	v_cvt_pk_bf16_f32 v73, v80, v81
	s_waitcnt lgkmcnt(11)
	v_mfma_f32_16x16x32_bf16 v[0:3], v[190:193], v[70:73], v[0:3]
	s_waitcnt lgkmcnt(10)
	v_mfma_f32_16x16x32_bf16 v[4:7], v[194:197], v[70:73], v[4:7]
	s_waitcnt lgkmcnt(9)
	v_mfma_f32_16x16x32_bf16 v[8:11], v[198:201], v[70:73], v[8:11]
	s_waitcnt lgkmcnt(8)
	v_mfma_f32_16x16x32_bf16 v[12:15], v[202:205], v[70:73], v[12:15]
	ds_read_b128 v[190:193], v247 offset:37248
	ds_read_b128 v[194:197], v247 offset:45696
	ds_read_b128 v[198:201], v247 offset:54144
	ds_read_b128 v[202:205], v247 offset:62592
	v_cvt_pk_bf16_f32 v48, v82, v83
	v_cvt_pk_bf16_f32 v49, v84, v85
	v_cvt_pk_bf16_f32 v50, v86, v87
	v_cvt_pk_bf16_f32 v51, v88, v89
	s_waitcnt lgkmcnt(11)
	v_mfma_f32_16x16x32_bf16 v[0:3], v[206:209], v[48:51], v[0:3]
	s_waitcnt lgkmcnt(10)
	v_mfma_f32_16x16x32_bf16 v[4:7], v[210:213], v[48:51], v[4:7]
	s_waitcnt lgkmcnt(9)
	v_mfma_f32_16x16x32_bf16 v[8:11], v[214:217], v[48:51], v[8:11]
	s_waitcnt lgkmcnt(8)
	v_mfma_f32_16x16x32_bf16 v[12:15], v[218:221], v[48:51], v[12:15]
	ds_read_b128 v[206:209], v247 offset:37312
	ds_read_b128 v[210:213], v247 offset:45760
	ds_read_b128 v[214:217], v247 offset:54208
	ds_read_b128 v[218:221], v247 offset:62656
	v_cvt_pk_bf16_f32 v64, v90, v91
	v_cvt_pk_bf16_f32 v65, v92, v93
	v_cvt_pk_bf16_f32 v66, v94, v95
	v_cvt_pk_bf16_f32 v67, v97, v100
	s_waitcnt lgkmcnt(11)
	v_mfma_f32_16x16x32_bf16 v[0:3], v[222:225], v[64:67], v[0:3]
	s_waitcnt lgkmcnt(10)
	v_mfma_f32_16x16x32_bf16 v[4:7], v[226:229], v[64:67], v[4:7]
	s_waitcnt lgkmcnt(9)
	v_mfma_f32_16x16x32_bf16 v[8:11], v[230:233], v[64:67], v[8:11]
	s_waitcnt lgkmcnt(8)
	v_mfma_f32_16x16x32_bf16 v[12:15], v[234:237], v[64:67], v[12:15]
	v_cvt_pk_bf16_f32 v40, v96, v98
	v_cvt_pk_bf16_f32 v41, v99, v101
	v_cvt_pk_bf16_f32 v42, v102, v104
	v_cvt_pk_bf16_f32 v43, v105, v108
	s_waitcnt lgkmcnt(7)
	v_mfma_f32_16x16x32_bf16 v[0:3], v[190:193], v[40:43], v[0:3]
	s_waitcnt lgkmcnt(6)
	v_mfma_f32_16x16x32_bf16 v[4:7], v[194:197], v[40:43], v[4:7]
	s_waitcnt lgkmcnt(5)
	v_mfma_f32_16x16x32_bf16 v[8:11], v[198:201], v[40:43], v[8:11]
	s_waitcnt lgkmcnt(4)
	v_mfma_f32_16x16x32_bf16 v[12:15], v[202:205], v[40:43], v[12:15]
	s_waitcnt lgkmcnt(0)
	v_add_f32_e32 v44, v114, v115
	v_cvt_pk_bf16_f32 v40, v103, v106
	v_cvt_pk_bf16_f32 v41, v107, v109
	v_cvt_pk_bf16_f32 v42, v110, v111
	v_cvt_pk_bf16_f32 v43, v112, v113
	s_waitcnt lgkmcnt(3)
	v_mfma_f32_16x16x32_bf16 v[0:3], v[206:209], v[40:43], v[0:3]
	s_waitcnt lgkmcnt(2)
	v_mfma_f32_16x16x32_bf16 v[4:7], v[210:213], v[40:43], v[4:7]
	s_waitcnt lgkmcnt(1)
	v_mfma_f32_16x16x32_bf16 v[8:11], v[214:217], v[40:43], v[8:11]
	s_waitcnt lgkmcnt(0)
	v_mfma_f32_16x16x32_bf16 v[12:15], v[218:221], v[40:43], v[12:15]
	v_add_f32_e32 v16, 0, v44
	v_div_scale_f32 v17, s[0:1], v16, v16, 1.0
	v_rcp_f32_e32 v18, v17
	v_div_scale_f32 v19, vcc, 1.0, v16, 1.0
	s_add_i32 s2, s2, s3
	v_fma_f32 v20, -v17, v18, 1.0
	v_fmac_f32_e32 v18, v20, v18
	v_mul_f32_e32 v20, v19, v18
	v_fma_f32 v21, -v17, v20, v19
	v_fmac_f32_e32 v20, v21, v18
	v_fma_f32 v17, -v17, v20, v19
	v_div_fmas_f32 v17, v17, v18, v20
	v_lshlrev_b64 v[18:19], 11, v[34:35]
	v_div_fixup_f32 v16, v17, v16, 1.0
	v_lshl_add_u64 v[18:19], s[42:43], 0, v[18:19]
	v_lshl_add_u64 v[18:19], v[18:19], 0, s[6:7]
	v_pk_mul_f32 v[2:3], v[16:17], v[2:3] op_sel_hi:[0,1]
	v_pk_mul_f32 v[0:1], v[16:17], v[0:1] op_sel_hi:[0,1]
	v_lshl_add_u64 v[18:19], v[38:39], 1, v[18:19]
	v_cvt_pk_bf16_f32 v0, v0, v1
	v_cvt_pk_bf16_f32 v1, v2, v3
	v_pk_mul_f32 v[2:3], v[16:17], v[4:5] op_sel_hi:[0,1]
	global_store_dwordx2 v[18:19], v[0:1], off
	v_pk_mul_f32 v[0:1], v[16:17], v[6:7] op_sel_hi:[0,1]
	v_cvt_pk_bf16_f32 v2, v2, v3
	v_cvt_pk_bf16_f32 v3, v0, v1
	global_store_dwordx2 v[18:19], v[2:3], off offset:32
	v_pk_mul_f32 v[2:3], v[16:17], v[8:9] op_sel_hi:[0,1]
	v_pk_mul_f32 v[0:1], v[16:17], v[10:11] op_sel_hi:[0,1]
	v_cvt_pk_bf16_f32 v2, v2, v3
	v_cvt_pk_bf16_f32 v3, v0, v1
	s_add_i32 s4, s4, s5
	s_add_i32 s11, s11, s10
	global_store_dwordx2 v[18:19], v[2:3], off offset:64
	v_pk_mul_f32 v[2:3], v[16:17], v[12:13] op_sel_hi:[0,1]
	s_cmpk_gt_i32 s2, 0xfff
	v_pk_mul_f32 v[0:1], v[16:17], v[14:15] op_sel_hi:[0,1]
	v_cvt_pk_bf16_f32 v2, v2, v3
	v_cvt_pk_bf16_f32 v3, v0, v1
	global_store_dwordx2 v[18:19], v[2:3], off offset:96
	s_cbranch_scc0 .LBB0_524
